# conv: nt hint on its 8 Y stores (consumed two phases later by GEMM-out); on top of v23
# baseline (speedup 1.0000x reference)
; __device__ __forceinline__ unsigned pk2(float lo, float hi) { return f2bf(lo) | (f2bf(hi) << 16); }
; __device__ __forceinline__ void conv_phase(const bf16* P1, const float* cw, bf16* Y, int gw, int NGW, int lane) {
;     ...
; #pragma unroll
;             for (int i = 0; i < 8; ++i) { const bf16* r = P1 + (size_t)(tok0 + i0 + i) * N1 + 8 * lane; bbv[i] = *(const v4u*)r; ccv[i] = *(const v4u*)(r + 512); }
;             __builtin_amdgcn_sched_barrier(0);
; #pragma unroll
;             for (int i = 0; i < 8; ++i) {
;                 const v4u bb = bbv[i], cc = ccv[i];
;                 float z0[8], y[8];
; #pragma unroll
;                 for (int k = 0; k < 4; ++k) { z0[2 * k] = bflo(cc[k]); z0[2 * k + 1] = bfhi(cc[k]); }
; #pragma unroll
;                 for (int k = 0; k < 4; ++k) {
;                     y[2 * k] = bflo(bb[k]) * (w0[2 * k] * z2[2 * k] + w1[2 * k] * z1[2 * k] + w2[2 * k] * z0[2 * k]);
;                     y[2 * k + 1] = bfhi(bb[k]) * (w0[2 * k + 1] * z2[2 * k + 1] + w1[2 * k + 1] * z1[2 * k + 1] + w2[2 * k + 1] * z0[2 * k + 1]);
;                 }
;                 v4u o; o.x = pk2(y[0], y[1]); o.y = pk2(y[2], y[3]); o.z = pk2(y[4], y[5]); o.w = pk2(y[6], y[7]);
;                 *(v4u*)(Y + (size_t)(tok0 + i0 + i) * D + 8 * lane) = o;
.LBB0_896:
	s_or_b32 s4, s4, s20
	s_or_b32 s6, s4, 1
	v_mad_i64_i32 v[24:25], s[68:69], s4, v229, v[80:81]
	s_or_b32 s18, s4, 2
	global_load_dwordx4 v[106:109], v[24:25], off
	global_load_dwordx4 v[110:113], v[24:25], off offset:1024
	v_mad_i64_i32 v[24:25], s[68:69], s6, v229, v[80:81]
	s_or_b32 s64, s4, 3
	global_load_dwordx4 v[72:75], v[24:25], off
	global_load_dwordx4 v[76:79], v[24:25], off offset:1024
	v_mad_i64_i32 v[24:25], s[68:69], s18, v229, v[80:81]
	s_or_b32 s66, s4, 4
	global_load_dwordx4 v[64:67], v[24:25], off
	global_load_dwordx4 v[68:71], v[24:25], off offset:1024
	v_mad_i64_i32 v[24:25], s[68:69], s64, v229, v[80:81]
	s_or_b32 s76, s4, 5
	global_load_dwordx4 v[56:59], v[24:25], off
	global_load_dwordx4 v[60:63], v[24:25], off offset:1024
	v_mad_i64_i32 v[24:25], s[68:69], s66, v229, v[80:81]
	s_or_b32 s78, s4, 6
	s_or_b32 s80, s4, 7
	global_load_dwordx4 v[48:51], v[24:25], off
	global_load_dwordx4 v[52:55], v[24:25], off offset:1024
	v_mad_i64_i32 v[24:25], s[68:69], s76, v229, v[80:81]
	global_load_dwordx4 v[40:43], v[24:25], off
	global_load_dwordx4 v[44:47], v[24:25], off offset:1024
	v_mad_i64_i32 v[24:25], s[68:69], s78, v229, v[80:81]
	v_mad_i64_i32 v[28:29], s[68:69], s80, v229, v[80:81]
	global_load_dwordx4 v[32:35], v[24:25], off
	global_load_dwordx4 v[36:39], v[24:25], off offset:1024
	s_nop 0
	global_load_dwordx4 v[24:27], v[28:29], off
	s_nop 0
	global_load_dwordx4 v[28:31], v[28:29], off offset:1024
	s_ashr_i32 s5, s4, 31
	s_ashr_i32 s81, s80, 31
	s_ashr_i32 s7, s6, 31
	s_ashr_i32 s19, s18, 31
	s_ashr_i32 s65, s64, 31
	s_ashr_i32 s67, s66, 31
	s_ashr_i32 s77, s76, 31
	s_ashr_i32 s79, s78, 31
	s_lshl_b64 s[74:75], s[4:5], 11
	s_lshl_b64 s[4:5], s[80:81], 11
	s_lshl_b64 s[72:73], s[6:7], 11
	s_lshl_b64 s[70:71], s[18:19], 11
	s_lshl_b64 s[68:69], s[64:65], 11
	s_lshl_b64 s[66:67], s[66:67], 11
	s_lshl_b64 s[64:65], s[76:77], 11
	s_lshl_b64 s[6:7], s[78:79], 11
	v_pk_mul_f32 v[92:93], v[84:85], v[92:93]
	s_waitcnt vmcnt(14)
	v_lshlrev_b32_e32 v103, 16, v111
	v_lshlrev_b32_e32 v102, 16, v110
	v_pk_fma_f32 v[92:93], v[86:87], v[94:95], v[92:93]
	v_pk_mul_f32 v[16:17], v[2:3], v[16:17]
	v_and_b32_e32 v101, 0xffff0000, v111
	v_and_b32_e32 v100, 0xffff0000, v110
	v_lshlrev_b32_e32 v111, 16, v107
	v_lshlrev_b32_e32 v110, 16, v106
	v_pk_fma_f32 v[92:93], v[8:9], v[102:103], v[92:93]
	v_pk_fma_f32 v[16:17], v[6:7], v[20:21], v[16:17]
	v_pk_mul_f32 v[110:111], v[92:93], v[110:111]
	v_and_b32_e32 v93, 0xffff0000, v107
	v_and_b32_e32 v92, 0xffff0000, v106
	v_pk_fma_f32 v[16:17], v[18:19], v[100:101], v[16:17]
	v_pk_mul_f32 v[88:89], v[10:11], v[88:89]
	v_pk_mul_f32 v[106:107], v[16:17], v[92:93]
	v_and_b32_e32 v17, 0xffff0000, v113
	v_and_b32_e32 v16, 0xffff0000, v112
	v_pk_mul_f32 v[96:97], v[0:1], v[96:97]
	v_pk_fma_f32 v[88:89], v[14:15], v[90:91], v[88:89]
	v_lshlrev_b32_e32 v93, 16, v113
	v_lshlrev_b32_e32 v92, 16, v112
	v_lshlrev_b32_e32 v113, 16, v109
	v_lshlrev_b32_e32 v112, 16, v108
	v_pk_fma_f32 v[96:97], v[4:5], v[98:99], v[96:97]
	v_and_b32_e32 v109, 0xffff0000, v109
	v_and_b32_e32 v108, 0xffff0000, v108
	v_pk_fma_f32 v[88:89], v[22:23], v[16:17], v[88:89]
	v_pk_fma_f32 v[96:97], v[12:13], v[92:93], v[96:97]
	v_pk_mul_f32 v[88:89], v[88:89], v[108:109]
	v_pk_mul_f32 v[96:97], v[96:97], v[112:113]
	v_bfe_u32 v108, v89, 16, 1
	v_bfe_u32 v109, v88, 16, 1
	v_bfe_u32 v112, v107, 16, 1
	v_bfe_u32 v113, v106, 16, 1
	v_add3_u32 v106, v106, v113, s59
	v_add3_u32 v107, v107, v112, s59
	v_add3_u32 v88, v88, v109, s59
	v_add3_u32 v89, v89, v108, s59
	v_bfe_u32 v108, v110, 16, 1
	v_bfe_u32 v109, v111, 16, 1
	v_bfe_u32 v112, v96, 16, 1
	v_bfe_u32 v113, v97, 16, 1
	v_add3_u32 v97, v97, v113, s59
	v_add3_u32 v96, v96, v112, s59
	v_add3_u32 v109, v111, v109, s59
	v_add3_u32 v108, v110, v108, s59
	v_lshrrev_b32_e32 v110, 16, v108
	v_lshrrev_b32_e32 v111, 16, v109
	v_lshrrev_b32_e32 v96, 16, v96
	v_lshrrev_b32_e32 v97, 16, v97
	v_and_or_b32 v109, v89, s60, v97
	v_and_or_b32 v108, v88, s60, v96
	v_and_or_b32 v107, v107, s60, v111
	v_and_or_b32 v106, v106, s60, v110
	v_lshl_add_u64 v[88:89], v[82:83], 0, s[74:75]
	global_store_dwordx4 v[88:89], v[106:109], off nt
	s_waitcnt vmcnt(13)
	v_lshlrev_b32_e32 v97, 16, v77
	v_lshlrev_b32_e32 v96, 16, v76
	v_pk_mul_f32 v[106:107], v[86:87], v[102:103]
	v_lshlrev_b32_e32 v89, 16, v73
	v_pk_fma_f32 v[94:95], v[84:85], v[94:95], v[106:107]
	v_lshlrev_b32_e32 v88, 16, v72
	v_pk_fma_f32 v[94:95], v[8:9], v[96:97], v[94:95]
	v_and_b32_e32 v77, 0xffff0000, v77
	v_pk_mul_f32 v[94:95], v[94:95], v[88:89]
	v_pk_mul_f32 v[88:89], v[6:7], v[100:101]
	v_and_b32_e32 v76, 0xffff0000, v76
	v_pk_fma_f32 v[20:21], v[2:3], v[20:21], v[88:89]
	v_pk_mul_f32 v[106:107], v[4:5], v[92:93]
	v_and_b32_e32 v73, 0xffff0000, v73
	v_and_b32_e32 v72, 0xffff0000, v72
	v_pk_fma_f32 v[20:21], v[18:19], v[76:77], v[20:21]
	v_lshlrev_b32_e32 v89, 16, v79
	v_lshlrev_b32_e32 v88, 16, v78
	v_pk_fma_f32 v[98:99], v[0:1], v[98:99], v[106:107]
	v_pk_mul_f32 v[72:73], v[20:21], v[72:73]
	v_and_b32_e32 v21, 0xffff0000, v79
	v_and_b32_e32 v20, 0xffff0000, v78
	v_lshlrev_b32_e32 v79, 16, v75
	v_lshlrev_b32_e32 v78, 16, v74
	v_pk_fma_f32 v[98:99], v[12:13], v[88:89], v[98:99]
	v_and_b32_e32 v75, 0xffff0000, v75
	v_pk_mul_f32 v[78:79], v[98:99], v[78:79]
	v_pk_mul_f32 v[98:99], v[14:15], v[16:17]
	v_and_b32_e32 v74, 0xffff0000, v74
	v_pk_fma_f32 v[90:91], v[10:11], v[90:91], v[98:99]
	v_bfe_u32 v98, v73, 16, 1
	v_pk_fma_f32 v[90:91], v[22:23], v[20:21], v[90:91]
	v_bfe_u32 v99, v72, 16, 1
	v_pk_mul_f32 v[74:75], v[90:91], v[74:75]
	v_add3_u32 v72, v72, v99, s59
	v_bfe_u32 v90, v75, 16, 1
	v_bfe_u32 v91, v74, 16, 1
	v_add3_u32 v73, v73, v98, s59
	v_add3_u32 v74, v74, v91, s59
	v_add3_u32 v75, v75, v90, s59
	v_bfe_u32 v90, v94, 16, 1
	v_bfe_u32 v91, v95, 16, 1
	v_bfe_u32 v98, v78, 16, 1
	v_bfe_u32 v99, v79, 16, 1
	v_add3_u32 v79, v79, v99, s59
	v_add3_u32 v78, v78, v98, s59
	v_add3_u32 v91, v95, v91, s59
	v_add3_u32 v90, v94, v90, s59
	v_lshrrev_b32_e32 v90, 16, v90
	v_lshrrev_b32_e32 v91, 16, v91
	v_lshrrev_b32_e32 v78, 16, v78
	v_lshrrev_b32_e32 v79, 16, v79
	v_and_or_b32 v75, v75, s60, v79
	v_and_or_b32 v74, v74, s60, v78
	v_and_or_b32 v73, v73, s60, v91
	v_and_or_b32 v72, v72, s60, v90
	v_lshl_add_u64 v[78:79], v[82:83], 0, s[72:73]
	global_store_dwordx4 v[78:79], v[72:75], off nt
	v_pk_mul_f32 v[78:79], v[86:87], v[96:97]
	v_pk_mul_f32 v[94:95], v[4:5], v[88:89]
	s_waitcnt vmcnt(12)
; __device__ __forceinline__ unsigned pk2(float lo, float hi) { return f2bf(lo) | (f2bf(hi) << 16); }
; __device__ __forceinline__ void conv_phase(const bf16* P1, const float* cw, bf16* Y, int gw, int NGW, int lane) {
;     ...
;             for (int i = 0; i < 8; ++i) {
;                 const v4u bb = bbv[i], cc = ccv[i];
;                 float z0[8], y[8];
; #pragma unroll
;                 for (int k = 0; k < 4; ++k) { z0[2 * k] = bflo(cc[k]); z0[2 * k + 1] = bfhi(cc[k]); }
; #pragma unroll
;                 for (int k = 0; k < 4; ++k) {
;                     y[2 * k] = bflo(bb[k]) * (w0[2 * k] * z2[2 * k] + w1[2 * k] * z1[2 * k] + w2[2 * k] * z0[2 * k]);
;                     y[2 * k + 1] = bfhi(bb[k]) * (w0[2 * k + 1] * z2[2 * k + 1] + w1[2 * k + 1] * z1[2 * k + 1] + w2[2 * k + 1] * z0[2 * k + 1]);
;                 }
;                 v4u o; o.x = pk2(y[0], y[1]); o.y = pk2(y[2], y[3]); o.z = pk2(y[4], y[5]); o.w = pk2(y[6], y[7]);
;                 *(v4u*)(Y + (size_t)(tok0 + i0 + i) * D + 8 * lane) = o;
; #pragma unroll
;                 for (int k = 0; k < 8; ++k) { z2[k] = z1[k]; z1[k] = z0[k]; }
	v_lshlrev_b32_e32 v75, 16, v69
	v_lshlrev_b32_e32 v74, 16, v68
	v_pk_fma_f32 v[78:79], v[84:85], v[102:103], v[78:79]
	v_lshlrev_b32_e32 v73, 16, v65
	v_lshlrev_b32_e32 v72, 16, v64
	v_pk_fma_f32 v[78:79], v[8:9], v[74:75], v[78:79]
	v_and_b32_e32 v69, 0xffff0000, v69
	v_pk_mul_f32 v[78:79], v[78:79], v[72:73]
	v_pk_mul_f32 v[72:73], v[6:7], v[76:77]
	v_and_b32_e32 v68, 0xffff0000, v68
	v_pk_fma_f32 v[72:73], v[2:3], v[100:101], v[72:73]
	v_and_b32_e32 v65, 0xffff0000, v65
	v_and_b32_e32 v64, 0xffff0000, v64
	v_pk_fma_f32 v[72:73], v[18:19], v[68:69], v[72:73]
	v_pk_fma_f32 v[92:93], v[0:1], v[92:93], v[94:95]
	v_pk_mul_f32 v[90:91], v[72:73], v[64:65]
	v_lshlrev_b32_e32 v73, 16, v71
	v_lshlrev_b32_e32 v72, 16, v70
	v_and_b32_e32 v65, 0xffff0000, v71
	v_and_b32_e32 v64, 0xffff0000, v70
	v_lshlrev_b32_e32 v71, 16, v67
	v_lshlrev_b32_e32 v70, 16, v66
	v_pk_fma_f32 v[92:93], v[12:13], v[72:73], v[92:93]
	v_and_b32_e32 v67, 0xffff0000, v67
	v_pk_mul_f32 v[70:71], v[92:93], v[70:71]
	v_pk_mul_f32 v[92:93], v[14:15], v[20:21]
	v_and_b32_e32 v66, 0xffff0000, v66
	v_pk_fma_f32 v[16:17], v[10:11], v[16:17], v[92:93]
	v_bfe_u32 v92, v91, 16, 1
	v_pk_fma_f32 v[16:17], v[22:23], v[64:65], v[16:17]
	v_bfe_u32 v93, v90, 16, 1
	v_pk_mul_f32 v[16:17], v[16:17], v[66:67]
	v_add3_u32 v90, v90, v93, s59
	v_bfe_u32 v66, v17, 16, 1
	v_bfe_u32 v67, v16, 16, 1
	v_add3_u32 v16, v16, v67, s59
	v_add3_u32 v17, v17, v66, s59
	v_bfe_u32 v66, v78, 16, 1
	v_bfe_u32 v67, v79, 16, 1
	v_add3_u32 v91, v91, v92, s59
	v_bfe_u32 v92, v70, 16, 1
	v_bfe_u32 v93, v71, 16, 1
	v_add3_u32 v67, v79, v67, s59
	v_add3_u32 v66, v78, v66, s59
	v_add3_u32 v71, v71, v93, s59
	v_add3_u32 v70, v70, v92, s59
	v_lshrrev_b32_e32 v66, 16, v66
	v_lshrrev_b32_e32 v67, 16, v67
	v_lshrrev_b32_e32 v70, 16, v70
	v_lshrrev_b32_e32 v71, 16, v71
	v_and_or_b32 v91, v91, s60, v67
	v_and_or_b32 v90, v90, s60, v66
	v_pk_mul_f32 v[66:67], v[86:87], v[74:75]
	v_and_or_b32 v93, v17, s60, v71
	v_and_or_b32 v92, v16, s60, v70
	v_lshl_add_u64 v[16:17], v[82:83], 0, s[70:71]
	s_waitcnt vmcnt(10)
	v_lshlrev_b32_e32 v71, 16, v61
	v_lshlrev_b32_e32 v70, 16, v60
	v_pk_fma_f32 v[66:67], v[84:85], v[96:97], v[66:67]
	global_store_dwordx4 v[16:17], v[90:93], off nt
	v_and_b32_e32 v17, 0xffff0000, v61
	v_and_b32_e32 v16, 0xffff0000, v60
	v_lshlrev_b32_e32 v61, 16, v57
	v_lshlrev_b32_e32 v60, 16, v56
	v_pk_fma_f32 v[66:67], v[8:9], v[70:71], v[66:67]
	v_and_b32_e32 v57, 0xffff0000, v57
	v_pk_mul_f32 v[60:61], v[66:67], v[60:61]
	v_pk_mul_f32 v[66:67], v[6:7], v[68:69]
	v_and_b32_e32 v56, 0xffff0000, v56
	v_pk_fma_f32 v[66:67], v[2:3], v[76:77], v[66:67]
	v_pk_mul_f32 v[78:79], v[4:5], v[72:73]
	v_pk_fma_f32 v[66:67], v[18:19], v[16:17], v[66:67]
	v_pk_fma_f32 v[78:79], v[0:1], v[88:89], v[78:79]
	v_pk_mul_f32 v[76:77], v[66:67], v[56:57]
	v_lshlrev_b32_e32 v67, 16, v63
	v_lshlrev_b32_e32 v66, 16, v62
	v_and_b32_e32 v57, 0xffff0000, v63
	v_and_b32_e32 v56, 0xffff0000, v62
	v_lshlrev_b32_e32 v63, 16, v59
	v_lshlrev_b32_e32 v62, 16, v58
	v_pk_fma_f32 v[78:79], v[12:13], v[66:67], v[78:79]
	v_and_b32_e32 v59, 0xffff0000, v59
	v_pk_mul_f32 v[62:63], v[78:79], v[62:63]
	v_pk_mul_f32 v[78:79], v[14:15], v[64:65]
	v_and_b32_e32 v58, 0xffff0000, v58
	v_pk_fma_f32 v[20:21], v[10:11], v[20:21], v[78:79]
	v_bfe_u32 v78, v77, 16, 1
	v_pk_fma_f32 v[20:21], v[22:23], v[56:57], v[20:21]
	v_bfe_u32 v79, v76, 16, 1
	v_pk_mul_f32 v[20:21], v[20:21], v[58:59]
	v_add3_u32 v76, v76, v79, s59
	v_bfe_u32 v58, v21, 16, 1
	v_bfe_u32 v59, v20, 16, 1
	v_add3_u32 v77, v77, v78, s59
	v_add3_u32 v20, v20, v59, s59
	v_add3_u32 v21, v21, v58, s59
	v_bfe_u32 v58, v60, 16, 1
	v_bfe_u32 v59, v61, 16, 1
	v_bfe_u32 v78, v62, 16, 1
	v_bfe_u32 v79, v63, 16, 1
	v_add3_u32 v63, v63, v79, s59
	v_add3_u32 v62, v62, v78, s59
	v_add3_u32 v59, v61, v59, s59
	v_add3_u32 v58, v60, v58, s59
	v_lshrrev_b32_e32 v58, 16, v58
	v_lshrrev_b32_e32 v59, 16, v59
	v_lshrrev_b32_e32 v60, 16, v62
	v_lshrrev_b32_e32 v61, 16, v63
	v_and_or_b32 v61, v21, s60, v61
	v_and_or_b32 v60, v20, s60, v60
	v_and_or_b32 v59, v77, s60, v59
	v_and_or_b32 v58, v76, s60, v58
	v_lshl_add_u64 v[20:21], v[82:83], 0, s[68:69]
	global_store_dwordx4 v[20:21], v[58:61], off nt
	s_waitcnt vmcnt(10)
	v_and_b32_e32 v21, 0xffff0000, v53
	v_and_b32_e32 v20, 0xffff0000, v52
	v_pk_mul_f32 v[58:59], v[86:87], v[70:71]
	v_lshlrev_b32_e32 v61, 16, v53
	v_lshlrev_b32_e32 v60, 16, v52
	v_pk_fma_f32 v[58:59], v[84:85], v[74:75], v[58:59]
	v_lshlrev_b32_e32 v53, 16, v49
	v_lshlrev_b32_e32 v52, 16, v48
	v_pk_fma_f32 v[58:59], v[8:9], v[60:61], v[58:59]
	v_and_b32_e32 v49, 0xffff0000, v49
	v_pk_mul_f32 v[62:63], v[58:59], v[52:53]
	v_pk_mul_f32 v[52:53], v[6:7], v[16:17]
	v_and_b32_e32 v48, 0xffff0000, v48
	v_pk_fma_f32 v[52:53], v[2:3], v[68:69], v[52:53]
	v_pk_mul_f32 v[68:69], v[4:5], v[66:67]
	v_pk_fma_f32 v[52:53], v[18:19], v[20:21], v[52:53]
	v_lshlrev_b32_e32 v59, 16, v55
	v_lshlrev_b32_e32 v58, 16, v54
	v_pk_fma_f32 v[68:69], v[0:1], v[72:73], v[68:69]
	v_pk_mul_f32 v[48:49], v[52:53], v[48:49]
	v_and_b32_e32 v53, 0xffff0000, v55
	v_and_b32_e32 v52, 0xffff0000, v54
	v_lshlrev_b32_e32 v55, 16, v51
	v_lshlrev_b32_e32 v54, 16, v50
	v_pk_fma_f32 v[68:69], v[12:13], v[58:59], v[68:69]
	v_and_b32_e32 v51, 0xffff0000, v51
	v_pk_mul_f32 v[54:55], v[68:69], v[54:55]
	v_pk_mul_f32 v[68:69], v[14:15], v[56:57]
	v_and_b32_e32 v50, 0xffff0000, v50
	v_pk_fma_f32 v[64:65], v[10:11], v[64:65], v[68:69]
	v_bfe_u32 v68, v49, 16, 1
	v_pk_fma_f32 v[64:65], v[22:23], v[52:53], v[64:65]
	v_bfe_u32 v69, v48, 16, 1
	v_pk_mul_f32 v[50:51], v[64:65], v[50:51]
	v_add3_u32 v48, v48, v69, s59
	v_bfe_u32 v64, v51, 16, 1
	v_bfe_u32 v65, v50, 16, 1
	v_add3_u32 v49, v49, v68, s59
	v_add3_u32 v50, v50, v65, s59
	v_add3_u32 v51, v51, v64, s59
	v_bfe_u32 v64, v62, 16, 1
	v_bfe_u32 v65, v63, 16, 1
	v_bfe_u32 v68, v54, 16, 1
	v_bfe_u32 v69, v55, 16, 1
	v_add3_u32 v55, v55, v69, s59
	v_add3_u32 v54, v54, v68, s59
	v_add3_u32 v63, v63, v65, s59
	v_add3_u32 v62, v62, v64, s59
	v_lshrrev_b32_e32 v62, 16, v62
	v_lshrrev_b32_e32 v63, 16, v63
	v_lshrrev_b32_e32 v54, 16, v54
	v_lshrrev_b32_e32 v55, 16, v55
	v_and_or_b32 v51, v51, s60, v55
	v_and_or_b32 v50, v50, s60, v54
	v_and_or_b32 v49, v49, s60, v63
	v_and_or_b32 v48, v48, s60, v62
	v_lshl_add_u64 v[54:55], v[82:83], 0, s[66:67]
	global_store_dwordx4 v[54:55], v[48:51], off nt
	v_pk_mul_f32 v[54:55], v[86:87], v[60:61]
	v_pk_mul_f32 v[62:63], v[4:5], v[58:59]
	s_waitcnt vmcnt(9)
; __device__ __forceinline__ unsigned pk2(float lo, float hi) { return f2bf(lo) | (f2bf(hi) << 16); }
; __device__ __forceinline__ void conv_phase(const bf16* P1, const float* cw, bf16* Y, int gw, int NGW, int lane) {
;     ...
;             for (int i = 0; i < 8; ++i) {
;                 const v4u bb = bbv[i], cc = ccv[i];
;                 float z0[8], y[8];
; #pragma unroll
;                 for (int k = 0; k < 4; ++k) { z0[2 * k] = bflo(cc[k]); z0[2 * k + 1] = bfhi(cc[k]); }
; #pragma unroll
;                 for (int k = 0; k < 4; ++k) {
;                     y[2 * k] = bflo(bb[k]) * (w0[2 * k] * z2[2 * k] + w1[2 * k] * z1[2 * k] + w2[2 * k] * z0[2 * k]);
;                     y[2 * k + 1] = bfhi(bb[k]) * (w0[2 * k + 1] * z2[2 * k + 1] + w1[2 * k + 1] * z1[2 * k + 1] + w2[2 * k + 1] * z0[2 * k + 1]);
;                 }
;                 v4u o; o.x = pk2(y[0], y[1]); o.y = pk2(y[2], y[3]); o.z = pk2(y[4], y[5]); o.w = pk2(y[6], y[7]);
;                 *(v4u*)(Y + (size_t)(tok0 + i0 + i) * D + 8 * lane) = o;
; #pragma unroll
;                 for (int k = 0; k < 8; ++k) { z2[k] = z1[k]; z1[k] = z0[k]; }
;             }
;             __builtin_amdgcn_sched_barrier(0);
;         }
;     }
	v_lshlrev_b32_e32 v51, 16, v45
	v_lshlrev_b32_e32 v50, 16, v44
	v_pk_fma_f32 v[54:55], v[84:85], v[70:71], v[54:55]
	v_lshlrev_b32_e32 v49, 16, v41
	v_lshlrev_b32_e32 v48, 16, v40
	v_pk_fma_f32 v[54:55], v[8:9], v[50:51], v[54:55]
	v_and_b32_e32 v45, 0xffff0000, v45
	v_pk_mul_f32 v[54:55], v[54:55], v[48:49]
	v_pk_mul_f32 v[48:49], v[6:7], v[20:21]
	v_and_b32_e32 v44, 0xffff0000, v44
	v_pk_fma_f32 v[16:17], v[2:3], v[16:17], v[48:49]
	v_and_b32_e32 v41, 0xffff0000, v41
	v_and_b32_e32 v40, 0xffff0000, v40
	v_pk_fma_f32 v[16:17], v[18:19], v[44:45], v[16:17]
	v_lshlrev_b32_e32 v49, 16, v47
	v_lshlrev_b32_e32 v48, 16, v46
	v_pk_fma_f32 v[62:63], v[0:1], v[66:67], v[62:63]
	v_pk_mul_f32 v[16:17], v[16:17], v[40:41]
	v_and_b32_e32 v41, 0xffff0000, v47
	v_and_b32_e32 v40, 0xffff0000, v46
	v_lshlrev_b32_e32 v47, 16, v43
	v_lshlrev_b32_e32 v46, 16, v42
	v_pk_fma_f32 v[62:63], v[12:13], v[48:49], v[62:63]
	v_and_b32_e32 v43, 0xffff0000, v43
	v_pk_mul_f32 v[46:47], v[62:63], v[46:47]
	v_pk_mul_f32 v[62:63], v[14:15], v[52:53]
	v_and_b32_e32 v42, 0xffff0000, v42
	v_pk_fma_f32 v[56:57], v[10:11], v[56:57], v[62:63]
	v_bfe_u32 v62, v17, 16, 1
	v_pk_fma_f32 v[56:57], v[22:23], v[40:41], v[56:57]
	v_bfe_u32 v63, v16, 16, 1
	v_pk_mul_f32 v[42:43], v[56:57], v[42:43]
	v_add3_u32 v16, v16, v63, s59
	v_bfe_u32 v56, v43, 16, 1
	v_bfe_u32 v57, v42, 16, 1
	v_add3_u32 v17, v17, v62, s59
	v_bfe_u32 v62, v46, 16, 1
	v_bfe_u32 v63, v47, 16, 1
	v_add3_u32 v42, v42, v57, s59
	v_add3_u32 v43, v43, v56, s59
	v_bfe_u32 v56, v54, 16, 1
	v_bfe_u32 v57, v55, 16, 1
	v_add3_u32 v47, v47, v63, s59
	v_add3_u32 v46, v46, v62, s59
	v_add3_u32 v55, v55, v57, s59
	v_add3_u32 v54, v54, v56, s59
	v_lshrrev_b32_e32 v46, 16, v46
	v_lshrrev_b32_e32 v47, 16, v47
	v_lshrrev_b32_e32 v54, 16, v54
	v_lshrrev_b32_e32 v55, 16, v55
	v_and_or_b32 v57, v43, s60, v47
	v_and_or_b32 v56, v42, s60, v46
	v_pk_mul_f32 v[42:43], v[86:87], v[50:51]
	v_and_or_b32 v55, v17, s60, v55
	v_and_or_b32 v54, v16, s60, v54
	v_lshl_add_u64 v[16:17], v[82:83], 0, s[64:65]
	s_waitcnt vmcnt(7)
	v_lshlrev_b32_e32 v93, 16, v37
	v_lshlrev_b32_e32 v92, 16, v36
	v_pk_fma_f32 v[42:43], v[84:85], v[60:61], v[42:43]
	global_store_dwordx4 v[16:17], v[54:57], off nt
	v_and_b32_e32 v17, 0xffff0000, v37
	v_and_b32_e32 v16, 0xffff0000, v36
	v_lshlrev_b32_e32 v37, 16, v33
	v_lshlrev_b32_e32 v36, 16, v32
	v_pk_fma_f32 v[42:43], v[8:9], v[92:93], v[42:43]
	v_lshlrev_b32_e32 v97, 16, v39
	v_pk_mul_f32 v[36:37], v[42:43], v[36:37]
	v_pk_mul_f32 v[42:43], v[6:7], v[44:45]
	v_lshlrev_b32_e32 v96, 16, v38
	v_pk_fma_f32 v[20:21], v[2:3], v[20:21], v[42:43]
	v_and_b32_e32 v89, 0xffff0000, v39
	v_and_b32_e32 v88, 0xffff0000, v38
	v_pk_mul_f32 v[38:39], v[4:5], v[48:49]
	v_and_b32_e32 v33, 0xffff0000, v33
	v_and_b32_e32 v32, 0xffff0000, v32
	v_pk_fma_f32 v[20:21], v[18:19], v[16:17], v[20:21]
	v_pk_fma_f32 v[38:39], v[0:1], v[58:59], v[38:39]
	v_pk_mul_f32 v[20:21], v[20:21], v[32:33]
	v_lshlrev_b32_e32 v33, 16, v35
	v_lshlrev_b32_e32 v32, 16, v34
	v_pk_fma_f32 v[38:39], v[12:13], v[96:97], v[38:39]
	v_and_b32_e32 v35, 0xffff0000, v35
	v_pk_mul_f32 v[32:33], v[38:39], v[32:33]
	v_pk_mul_f32 v[38:39], v[14:15], v[40:41]
	v_and_b32_e32 v34, 0xffff0000, v34
	v_pk_fma_f32 v[38:39], v[10:11], v[52:53], v[38:39]
	v_bfe_u32 v42, v21, 16, 1
	v_pk_fma_f32 v[38:39], v[22:23], v[88:89], v[38:39]
	v_bfe_u32 v43, v20, 16, 1
	v_pk_mul_f32 v[34:35], v[38:39], v[34:35]
	v_add3_u32 v20, v20, v43, s59
	v_bfe_u32 v38, v35, 16, 1
	v_bfe_u32 v39, v34, 16, 1
	v_add3_u32 v21, v21, v42, s59
	v_add3_u32 v34, v34, v39, s59
	v_add3_u32 v35, v35, v38, s59
	v_bfe_u32 v38, v36, 16, 1
	v_bfe_u32 v39, v37, 16, 1
	v_bfe_u32 v42, v32, 16, 1
	v_bfe_u32 v43, v33, 16, 1
	v_add3_u32 v33, v33, v43, s59
	v_add3_u32 v32, v32, v42, s59
	v_add3_u32 v37, v37, v39, s59
	v_add3_u32 v36, v36, v38, s59
	v_lshrrev_b32_e32 v36, 16, v36
	v_lshrrev_b32_e32 v37, 16, v37
	v_lshrrev_b32_e32 v32, 16, v32
	v_lshrrev_b32_e32 v33, 16, v33
	v_and_or_b32 v35, v35, s60, v33
	v_and_or_b32 v34, v34, s60, v32
	v_and_or_b32 v33, v21, s60, v37
	v_and_or_b32 v32, v20, s60, v36
	v_lshl_add_u64 v[20:21], v[82:83], 0, s[6:7]
	global_store_dwordx4 v[20:21], v[32:35], off nt
	s_waitcnt vmcnt(7)
	v_lshlrev_b32_e32 v95, 16, v29
	v_lshlrev_b32_e32 v94, 16, v28
	v_pk_mul_f32 v[32:33], v[86:87], v[92:93]
	v_and_b32_e32 v21, 0xffff0000, v29
	v_pk_fma_f32 v[32:33], v[84:85], v[50:51], v[32:33]
	v_and_b32_e32 v20, 0xffff0000, v28
	v_lshlrev_b32_e32 v29, 16, v25
	v_lshlrev_b32_e32 v28, 16, v24
	v_pk_fma_f32 v[32:33], v[8:9], v[94:95], v[32:33]
	v_and_b32_e32 v25, 0xffff0000, v25
	v_pk_mul_f32 v[28:29], v[32:33], v[28:29]
	v_pk_mul_f32 v[32:33], v[6:7], v[16:17]
	v_and_b32_e32 v24, 0xffff0000, v24
	v_pk_fma_f32 v[32:33], v[2:3], v[44:45], v[32:33]
	v_lshlrev_b32_e32 v99, 16, v31
	v_pk_fma_f32 v[32:33], v[18:19], v[20:21], v[32:33]
	v_lshlrev_b32_e32 v98, 16, v30
	v_pk_mul_f32 v[24:25], v[32:33], v[24:25]
	v_pk_mul_f32 v[32:33], v[4:5], v[96:97]
	v_and_b32_e32 v91, 0xffff0000, v31
	v_pk_fma_f32 v[32:33], v[0:1], v[48:49], v[32:33]
	v_and_b32_e32 v90, 0xffff0000, v30
	v_lshlrev_b32_e32 v31, 16, v27
	v_lshlrev_b32_e32 v30, 16, v26
	v_pk_fma_f32 v[32:33], v[12:13], v[98:99], v[32:33]
	v_and_b32_e32 v27, 0xffff0000, v27
	v_pk_mul_f32 v[30:31], v[32:33], v[30:31]
	v_pk_mul_f32 v[32:33], v[14:15], v[88:89]
	v_and_b32_e32 v26, 0xffff0000, v26
	v_pk_fma_f32 v[32:33], v[10:11], v[40:41], v[32:33]
	v_bfe_u32 v34, v25, 16, 1
	v_pk_fma_f32 v[32:33], v[22:23], v[90:91], v[32:33]
	v_bfe_u32 v35, v24, 16, 1
	v_pk_mul_f32 v[26:27], v[32:33], v[26:27]
	v_add3_u32 v24, v24, v35, s59
	v_bfe_u32 v32, v27, 16, 1
	v_bfe_u32 v33, v26, 16, 1
	v_add3_u32 v25, v25, v34, s59
	v_add3_u32 v26, v26, v33, s59
	v_add3_u32 v27, v27, v32, s59
	v_bfe_u32 v32, v28, 16, 1
	v_bfe_u32 v33, v29, 16, 1
	v_bfe_u32 v34, v30, 16, 1
	v_bfe_u32 v35, v31, 16, 1
	v_add3_u32 v31, v31, v35, s59
	v_add3_u32 v30, v30, v34, s59
	v_add3_u32 v29, v29, v33, s59
	v_add3_u32 v28, v28, v32, s59
	v_lshrrev_b32_e32 v28, 16, v28
	v_lshrrev_b32_e32 v29, 16, v29
	v_lshrrev_b32_e32 v30, 16, v30
	v_lshrrev_b32_e32 v31, 16, v31
	v_and_or_b32 v27, v27, s60, v31
	v_and_or_b32 v26, v26, s60, v30
	v_and_or_b32 v25, v25, s60, v29
	v_and_or_b32 v24, v24, s60, v28
	v_lshl_add_u64 v[28:29], v[82:83], 0, s[4:5]
	global_store_dwordx4 v[28:29], v[24:27], off nt
	s_mov_b32 s4, 8
	s_andn2_b64 vcc, exec, s[2:3]
	s_mov_b64 s[2:3], 0
	s_cbranch_vccz .LBB0_896
	s_add_i32 s8, s8, s9
	s_cmpk_gt_i32 s8, 0x7ff
	s_cbranch_scc0 .LBB0_892
